# p0wt: phase-0 converted-weight stores write-through (sc1) so the first release fence has little to write back
# speedup vs baseline: 1.0027x; 1.0027x over previous
;   __host__ __device__ __forceinline__ float* dn() const { return (float*)(wsl() + OFF_DN); }
; __device__ __forceinline__ void wstore(const WDesc& d, int wi, int tid, const float4 (&v)[4], bf16_t* s) {
;   int local = wi - d.item_start;
;   int tiles = d.ntn * d.nkt;
;   int bi = local / tiles, rem = local - bi * tiles;
;   int kt = rem / d.ntn, nt = rem - kt * d.ntn;
;   int k0 = kt * 128, n0 = nt * 64;
; #pragma unroll
;   for (int i = 0; i < 4; ++i) {
;     int idx = tid + i * NTHR;
;     int k = idx >> 4, n4 = (idx & 15) * 4;
;     s[wsw(n4 + 0, k)] = f2bf(v[i].x);
;     s[wsw(n4 + 1, k)] = f2bf(v[i].y);
;     s[wsw(n4 + 2, k)] = f2bf(v[i].z);
;     s[wsw(n4 + 3, k)] = f2bf(v[i].w);
;   }
;   __syncthreads();
; #pragma unroll
;   for (int i = 0; i < 2; ++i) {
;     int idx = tid + i * NTHR;
;     int n = idx >> 4, kc = (idx & 15) * 8;
;     int gidx = bi * d.N + n0 + n;
;     int drow = gidx;
;     if (d.mode != 0) drow = (gidx >> 6) * 128 + ((gidx & 63) >> 4) * 32 + (gidx & 15) + (d.mode == 2 ? 16 : 0);
;     uint4 o = *(const uint4*)(s + wsw(n, kc));
;     *(uint4*)(d.dst + (size_t)drow * d.K + k0 + kc) = o;
;   }
; __device__ __forceinline__ void p0_phase(const Params& p, char* smem) {
;     ...
;       wstore(d, wi, tid, v, s);
; #pragma unroll
;       for (int i = 0; i < 4; ++i) v[i] = vn[i];
;       d = dn; wi = win;
.LBB0_1000:
	s_mul_i32 s8, s18, s21
	s_abs_i32 s9, s8
	v_cvt_f32_u32_e32 v37, s9
	s_sub_i32 s10, s15, s20
	s_ashr_i32 s10, s10, 31
	s_sub_i32 s12, s10, s20
	v_rcp_iflag_f32_e32 v37, v37
	s_ashr_i32 s11, s8, 31
	s_add_i32 s12, s15, s12
	s_xor_b32 s11, s10, s11
	v_mul_f32_e32 v37, 0x4f7ffffe, v37
	v_cvt_u32_f32_e32 v37, v37
	s_xor_b32 s10, s12, s10
	s_sub_i32 s13, 0, s9
	v_readfirstlane_b32 s12, v37
	v_cvt_f32_u32_e32 v37, s18
	s_mul_i32 s13, s13, s12
	s_mul_hi_u32 s13, s12, s13
	s_add_i32 s12, s12, s13
	v_rcp_iflag_f32_e32 v37, v37
	s_mul_hi_u32 s12, s10, s12
	s_mul_i32 s13, s12, s9
	s_sub_i32 s10, s10, s13
	s_add_i32 s27, s12, 1
	s_sub_i32 s13, s10, s9
	v_mul_f32_e32 v37, 0x4f7ffffe, v37
	s_cmp_ge_u32 s10, s9
	v_cvt_u32_f32_e32 v37, v37
	s_cselect_b32 s12, s27, s12
	s_cselect_b32 s10, s13, s10
	s_add_i32 s13, s12, 1
	s_cmp_ge_u32 s10, s9
	s_cselect_b32 s9, s13, s12
	v_readfirstlane_b32 s13, v37
	s_waitcnt vmcnt(0)
	v_bfe_u32 v37, v0, 16, 1
	v_add3_u32 v0, v0, v37, s28
	ds_write_b16_d16_hi v44, v0
	v_bfe_u32 v0, v1, 16, 1
	v_add3_u32 v0, v1, v0, s28
	ds_write_b16_d16_hi v44, v0 offset:272
	v_bfe_u32 v0, v2, 16, 1
	s_xor_b32 s9, s9, s11
	v_add3_u32 v0, v2, v0, s28
	s_sub_i32 s10, s9, s11
	ds_write_b16_d16_hi v44, v0 offset:544
	v_bfe_u32 v0, v3, 16, 1
	s_mul_i32 s9, s21, s10
	v_add3_u32 v0, v3, v0, s28
	s_mul_i32 s11, s18, s9
	ds_write_b16_d16_hi v44, v0 offset:816
	v_bfe_u32 v0, v4, 16, 1
	s_add_i32 s11, s11, s20
	v_add3_u32 v0, v4, v0, s28
	s_sub_i32 s11, s15, s11
	ds_write_b16_d16_hi v45, v0
	v_bfe_u32 v0, v5, 16, 1
	s_mul_i32 s8, s10, s8
	s_ashr_i32 s11, s11, 31
	v_add3_u32 v0, v5, v0, s28
	s_sub_i32 s8, s11, s8
	s_sub_i32 s12, 0, s18
	ds_write_b16_d16_hi v45, v0 offset:272
	v_bfe_u32 v0, v6, 16, 1
	s_sub_i32 s8, s8, s20
	s_mul_i32 s12, s12, s13
	v_add3_u32 v0, v6, v0, s28
	s_add_i32 s8, s15, s8
	s_mul_hi_u32 s12, s13, s12
	ds_write_b16_d16_hi v45, v0 offset:544
	v_bfe_u32 v0, v7, 16, 1
	s_xor_b32 s8, s8, s11
	s_add_i32 s13, s13, s12
	v_add3_u32 v0, v7, v0, s28
	s_mul_hi_u32 s12, s8, s13
	ds_write_b16_d16_hi v45, v0 offset:816
	v_bfe_u32 v0, v8, 16, 1
	s_mul_i32 s13, s12, s18
	v_add3_u32 v0, v8, v0, s28
	s_sub_i32 s8, s8, s13
	ds_write_b16_d16_hi v46, v0
	v_bfe_u32 v0, v9, 16, 1
	s_add_i32 s13, s12, 1
	s_sub_i32 s21, s8, s18
	v_add3_u32 v0, v9, v0, s28
	s_cmp_ge_u32 s8, s18
	ds_write_b16_d16_hi v46, v0 offset:272
	v_bfe_u32 v0, v10, 16, 1
	s_cselect_b32 s12, s13, s12
	v_add3_u32 v0, v10, v0, s28
	s_cselect_b32 s8, s21, s8
	s_add_i32 s13, s12, 1
	ds_write_b16_d16_hi v46, v0 offset:544
	v_bfe_u32 v0, v11, 16, 1
	s_cmp_ge_u32 s8, s18
	v_add3_u32 v0, v11, v0, s28
	s_cselect_b32 s8, s13, s12
	ds_write_b16_d16_hi v46, v0 offset:816
	v_bfe_u32 v0, v12, 16, 1
	s_xor_b32 s12, s8, s11
	v_add3_u32 v0, v12, v0, s28
	s_sub_i32 s9, s11, s9
	ds_write_b16_d16_hi v47, v0
	v_bfe_u32 v0, v13, 16, 1
	s_sub_i32 s9, s9, s12
	v_add3_u32 v0, v13, v0, s28
	s_mul_i32 s9, s18, s9
	ds_write_b16_d16_hi v47, v0 offset:272
	v_bfe_u32 v0, v14, 16, 1
	s_sub_i32 s9, s9, s20
	s_sub_i32 s8, s12, s11
	v_add3_u32 v0, v14, v0, s28
	s_add_i32 s9, s15, s9
	s_lshl_b32 s8, s8, 7
	ds_write_b16_d16_hi v47, v0 offset:544
	v_bfe_u32 v0, v15, 16, 1
	s_lshl_b32 s11, s9, 6
	s_mul_i32 s10, s10, s17
	v_add3_u32 v0, v15, v0, s28
	s_ashr_i32 s9, s8, 31
	s_add_i32 s12, s11, s10
	ds_write_b16_d16_hi v47, v0 offset:816
	v_add_u32_e32 v0, s12, v33
	s_cmp_eq_u32 s16, 0
	s_cselect_b64 vcc, -1, 0
	v_lshlrev_b32_e32 v1, 1, v0
	s_cmp_eq_u32 s16, 2
	v_and_b32_e32 v1, 0xffffffe0, v1
	v_and_b32_e32 v2, 15, v0
	s_cselect_b32 s13, 16, 0
	v_or3_b32 v1, v2, v1, s13
	v_cndmask_b32_e32 v4, v1, v0, vcc
	v_ashrrev_i32_e32 v7, 31, v4
	v_mad_u64_u32 v[4:5], s[10:11], v4, s19, 0
	v_mov_b32_e32 v6, v5
	s_waitcnt lgkmcnt(0)
	s_barrier
	ds_read_b128 v[0:3], v48
	v_mad_u64_u32 v[6:7], s[10:11], v7, s19, v[6:7]
	v_mov_b32_e32 v5, v6
	v_lshl_add_u64 v[4:5], v[4:5], 1, s[48:49]
	s_lshl_b64 s[8:9], s[8:9], 1
	v_lshl_add_u64 v[4:5], v[4:5], 0, s[8:9]
	v_mov_b32_e32 v37, v167
	v_lshl_add_u64 v[8:9], v[4:5], 0, v[36:37]
	ds_read_b128 v[4:7], v49
	s_waitcnt lgkmcnt(1)
	global_store_dwordx4 v[8:9], v[0:3], off sc1
	s_mov_b32 s15, s22
	s_mov_b32 s20, s25
	v_add_u32_e32 v0, s12, v35
	v_lshlrev_b32_e32 v1, 1, v0
	v_and_b32_e32 v1, 0xffffffe0, v1
	v_and_b32_e32 v2, 15, v0
	v_or3_b32 v1, v2, v1, s13
	v_cndmask_b32_e32 v0, v1, v0, vcc
	v_ashrrev_i32_e32 v3, 31, v0
	v_mad_u64_u32 v[0:1], s[10:11], v0, s19, 0
	v_mov_b32_e32 v2, v1
	v_mad_u64_u32 v[2:3], s[10:11], v3, s19, v[2:3]
	v_mov_b32_e32 v1, v2
	v_lshl_add_u64 v[0:1], v[0:1], 1, s[48:49]
	v_lshl_add_u64 v[0:1], v[0:1], 0, s[8:9]
	v_lshl_add_u64 v[0:1], v[0:1], 0, v[36:37]
	s_waitcnt lgkmcnt(0)
	global_store_dwordx4 v[0:1], v[4:7], off sc1
	s_andn2_b64 vcc, exec, s[4:5]
	s_mov_b32 s16, s3
	s_mov_b32 s21, s24
	s_mov_b32 s18, s23
	s_mov_b32 s17, s2
	s_mov_b32 s19, s26
	s_mov_b64 s[48:49], s[6:7]
	v_mov_b64_e32 v[10:11], v[26:27]
	v_mov_b64_e32 v[8:9], v[24:25]
	v_mov_b64_e32 v[6:7], v[22:23]
	v_mov_b64_e32 v[4:5], v[20:21]
	v_mov_b64_e32 v[2:3], v[18:19]
	v_mov_b64_e32 v[0:1], v[16:17]
	v_mov_b32_e32 v14, v30
	v_mov_b32_e32 v15, v31
	v_mov_b32_e32 v12, v28
	v_mov_b32_e32 v13, v29
	s_barrier
	s_cbranch_vccz .LBB0_1055
